# FFN1 conv parameters staged in LDS behind the existing parameter wait (one extra workgroup barrier per tile) instead of an early drain
# speedup vs baseline: 1.0103x; 1.0103x over previous
;     __device__ __forceinline__ void operator()(AccRef acc, const Unit& u, int wr, int wc, int fr, int fq) const {
;     ...
;         float* rawu = raw + (size_t)(u.pm * 22 + u.pn) * 1024;
;         if (wr == 0 && fr == 0) {
; #pragma unroll
;             for (int bj = 0; bj < 2; ++bj)
; #pragma unroll
;                 for (int n = 0; n < 2; ++n) { *(f32x4*)(rawu + 0 * 256 + bj * 128 + clb + 4 * n) = acc[0][bj][0][n]; *(f32x4*)(rawu + 1 * 256 + bj * 128 + clb + 4 * n) = acc[0][bj][1][n]; }
;         }
;         if (wr == 1 && fr == 15) {
; #pragma unroll
;             for (int bj = 0; bj < 2; ++bj)
; #pragma unroll
;                 for (int n = 0; n < 2; ++n) { *(f32x4*)(rawu + 2 * 256 + bj * 128 + clb + 4 * n) = acc[1][bj][2][n]; *(f32x4*)(rawu + 3 * 256 + bj * 128 + clb + 4 * n) = acc[1][bj][3][n]; }
;         }
;         asm volatile("s_waitcnt lgkmcnt(0)" ::: "memory"); __builtin_amdgcn_s_barrier(); __builtin_amdgcn_s_barrier(); asm volatile("" ::: "memory");
;         const int hc0 = 128 * u.pn + clb, row0 = u.pm * 256 + wr * 64 + 4 * fr;
; #pragma unroll
;         for (int n = 0; n < 2; ++n) {
;             const f32x4 w0v = cwv[n][0], w1v = cwv[n][1], w2v = cwv[n][2], bvv = cwv[n][3], w0g = cwv[n][4], w1g = cwv[n][5], w2g = cwv[n][6], bvg = cwv[n][7];
; #pragma unroll
;             for (int ai = 0; ai < 2; ++ai) {
;                 if (n == 0 && ai == 0) {
;                     asm volatile("" ::: "memory");
;                     const float* cv = cw + hc0 + 4; const float* cg = cv + FH; const float* bp = cb + hc0 + 4;
;                     cwv[1][0] = *(const f32x4*)(cv); cwv[1][1] = *(const f32x4*)(cv + F2); cwv[1][2] = *(const f32x4*)(cv + 2 * F2); cwv[1][3] = *(const f32x4*)(bp);
;                     cwv[1][4] = *(const f32x4*)(cg); cwv[1][5] = *(const f32x4*)(cg + F2); cwv[1][6] = *(const f32x4*)(cg + 2 * F2); cwv[1][7] = *(const f32x4*)(bp + FH);
;                     asm volatile("" ::: "memory"); }
;                 f32x4 h2v = (f32x4){0.f, 0.f, 0.f, 0.f}, h3v = h2v, h2g = h2v, h3g = h2v;
;                 const int pb = ai * 2 + wr - 1;
;                 if (pb >= 0 && fr == 0) { const LAS float* xp = xch + (pb * 2) * 256 + clb + 4 * n;
;                     h2v = *(const LAS f32x4*)(xp); h3v = *(const LAS f32x4*)(xp + 256); h2g = *(const LAS f32x4*)(xp + 128); h3g = *(const LAS f32x4*)(xp + 256 + 128); }
.LBB0_312:
	s_or_b64 exec, exec, s[38:39]
	s_mul_i32 s25, s34, 22
	s_add_i32 s38, s25, s35
	s_ashr_i32 s39, s38, 31
	s_lshl_b64 s[38:39], s[38:39], 12
	s_add_u32 s38, s64, s38
	s_addc_u32 s39, s65, s39
	v_lshlrev_b32_e32 v96, 2, v218
	v_or_b32_e32 v232, s36, v218
	v_ashrrev_i32_e32 v233, 31, v232
	v_lshlrev_b64 v[96:97], 2, v[232:233]
	v_lshl_add_u64 v[120:121], s[56:57], 0, v[96:97]
	v_add_co_u32_e32 v100, vcc, 0x5000, v120
	s_waitcnt lgkmcnt(0)
	s_barrier
	s_nop 0
	v_addc_co_u32_e32 v101, vcc, 0, v121, vcc
	v_add_co_u32_e32 v104, vcc, 0xb000, v120
	s_barrier
	s_nop 0
	v_addc_co_u32_e32 v105, vcc, 0, v121, vcc
	v_add_co_u32_e32 v112, vcc, s49, v120
	v_lshl_add_u64 v[124:125], s[58:59], 0, v[96:97]
	s_nop 0
	v_addc_co_u32_e32 v113, vcc, 0, v121, vcc
	v_add_co_u32_e32 v116, vcc, 0x8000, v120
	s_nop 0
	s_nop 0
	v_addc_co_u32_e32 v117, vcc, 0, v121, vcc
	v_add_co_u32_e32 v120, vcc, 0xd000, v120
	s_nop 0
	s_nop 0
	v_addc_co_u32_e32 v121, vcc, 0, v121, vcc
	v_add_co_u32_e32 v124, vcc, 0x2000, v124
	s_nop 0
	s_nop 0
	v_addc_co_u32_e32 v125, vcc, 0, v125, vcc
	v_mov_b32_e32 v192, 0
	v_mov_b32_e32 v198, 0
	v_mov_b32_e32 v199, 0
	v_mov_b32_e32 v200, 0
	v_mov_b32_e32 v201, 0
	v_mov_b32_e32 v206, 0
	v_mov_b32_e32 v207, 0
	v_mov_b32_e32 v208, 0
	v_mov_b32_e32 v209, 0
	v_mov_b32_e32 v194, 0
	v_mov_b32_e32 v195, 0
	v_mov_b32_e32 v196, 0
	v_mov_b32_e32 v197, 0
	v_mov_b32_e32 v202, 0
	v_mov_b32_e32 v203, 0
	v_mov_b32_e32 v204, 0
	v_mov_b32_e32 v205, 0
	s_and_saveexec_b64 s[36:37], s[18:19]
	s_cbranch_execz .LBB0_318
	ds_read_b128 v[202:205], v238
	ds_read_b128 v[206:209], v238 offset:512
	ds_read_b128 v[194:197], v238 offset:1024
	ds_read_b128 v[198:201], v238 offset:1536
.LBB0_318:
	s_or_b64 exec, exec, s[36:37]
	s_waitcnt lgkmcnt(0)
	v_mov_b32_dpp v198, v140 row_shr:1 row_mask:0xf bank_mask:0xf
	v_mov_b32_dpp v199, v141 row_shr:1 row_mask:0xf bank_mask:0xf
	s_waitcnt vmcnt(0)
	s_bitcmp1_b32 s99, 8
	s_cbranch_scc1 .Lcw309_nostage
	v_and_b32_e32 v107, 0xff, v219
	v_lshlrev_b32_e32 v107, 4, v107
	v_add_u32_e32 v107, 0x22000, v107
	ds_write_b128 v107, v[108:111]
.Lcw309_nostage:
	s_waitcnt lgkmcnt(0)
	s_barrier
	v_and_b32_e32 v253, 0xf0, v219
	v_lshlrev_b32_e32 v253, 4, v253
	v_add_u32_e32 v253, 0x22000, v253
	ds_read_b128 v[160:163], v253
	ds_read_b128 v[164:167], v253 offset:16
	ds_read_b128 v[168:171], v253 offset:32
	ds_read_b128 v[172:175], v253 offset:48
	ds_read_b128 v[176:179], v253 offset:64
	ds_read_b128 v[180:183], v253 offset:80
	ds_read_b128 v[184:187], v253 offset:96
	ds_read_b128 v[188:191], v253 offset:112
	ds_read_b128 v[96:99], v253 offset:128
	ds_read_b128 v[100:103], v253 offset:144
	ds_read_b128 v[104:107], v253 offset:160
	ds_read_b128 v[108:111], v253 offset:176
	ds_read_b128 v[112:115], v253 offset:192
	ds_read_b128 v[116:119], v253 offset:208
	ds_read_b128 v[120:123], v253 offset:224
	ds_read_b128 v[124:127], v253 offset:240
	s_waitcnt lgkmcnt(0)
	v_lshlrev_b32_e32 v253, 2, v218
	s_and_saveexec_b64 s[40:41], s[10:11]
	s_cbranch_execz .LBB0_314
	global_store_dwordx4 v253, v[156:159], s[38:39]
	global_store_dwordx4 v253, v[144:147], s[38:39] offset:1024
	global_store_dwordx4 v253, v[60:63], s[38:39] offset:16
	global_store_dwordx4 v253, v[48:51], s[38:39] offset:1040
	global_store_dwordx4 v253, v[152:155], s[38:39] offset:512
	global_store_dwordx4 v253, v[132:135], s[38:39] offset:1536
	global_store_dwordx4 v253, v[56:59], s[38:39] offset:528
	global_store_dwordx4 v253, v[36:39], s[38:39] offset:1552

;     __device__ __forceinline__ void operator()(AccRef acc, const Unit& u, int wr, int wc, int fr, int fq) const {
;     ...
;         float* rawu = raw + (size_t)(u.pm * 22 + u.pn) * 1024;
;         if (wr == 0 && fr == 0) {
; #pragma unroll
;             for (int bj = 0; bj < 2; ++bj)
; #pragma unroll
;                 for (int n = 0; n < 2; ++n) { *(f32x4*)(rawu + 0 * 256 + bj * 128 + clb + 4 * n) = acc[0][bj][0][n]; *(f32x4*)(rawu + 1 * 256 + bj * 128 + clb + 4 * n) = acc[0][bj][1][n]; }
;         }
;         if (wr == 1 && fr == 15) {
; #pragma unroll
;             for (int bj = 0; bj < 2; ++bj)
; #pragma unroll
;                 for (int n = 0; n < 2; ++n) { *(f32x4*)(rawu + 2 * 256 + bj * 128 + clb + 4 * n) = acc[1][bj][2][n]; *(f32x4*)(rawu + 3 * 256 + bj * 128 + clb + 4 * n) = acc[1][bj][3][n]; }
;         }
;         asm volatile("s_waitcnt lgkmcnt(0)" ::: "memory"); __builtin_amdgcn_s_barrier(); __builtin_amdgcn_s_barrier(); asm volatile("" ::: "memory");
;         const int hc0 = 128 * u.pn + clb, row0 = u.pm * 256 + wr * 64 + 4 * fr;
; #pragma unroll
;         for (int n = 0; n < 2; ++n) {
;             const f32x4 w0v = cwv[n][0], w1v = cwv[n][1], w2v = cwv[n][2], bvv = cwv[n][3], w0g = cwv[n][4], w1g = cwv[n][5], w2g = cwv[n][6], bvg = cwv[n][7];
; #pragma unroll
;             for (int ai = 0; ai < 2; ++ai) {
;                 if (n == 0 && ai == 0) {
;                     asm volatile("" ::: "memory");
;                     const float* cv = cw + hc0 + 4; const float* cg = cv + FH; const float* bp = cb + hc0 + 4;
;                     cwv[1][0] = *(const f32x4*)(cv); cwv[1][1] = *(const f32x4*)(cv + F2); cwv[1][2] = *(const f32x4*)(cv + 2 * F2); cwv[1][3] = *(const f32x4*)(bp);
;                     cwv[1][4] = *(const f32x4*)(cg); cwv[1][5] = *(const f32x4*)(cg + F2); cwv[1][6] = *(const f32x4*)(cg + 2 * F2); cwv[1][7] = *(const f32x4*)(bp + FH);
;                     asm volatile("" ::: "memory"); }
;                 f32x4 h2v = (f32x4){0.f, 0.f, 0.f, 0.f}, h3v = h2v, h2g = h2v, h3g = h2v;
;                 const int pb = ai * 2 + wr - 1;
;                 if (pb >= 0 && fr == 0) { const LAS float* xp = xch + (pb * 2) * 256 + clb + 4 * n;
;                     h2v = *(const LAS f32x4*)(xp); h3v = *(const LAS f32x4*)(xp + 256); h2g = *(const LAS f32x4*)(xp + 128); h3g = *(const LAS f32x4*)(xp + 256 + 128); }
.LBB0_761:
	s_or_b64 exec, exec, s[44:45]
	s_mul_i32 s31, s40, 22
	s_add_i32 s44, s31, s41
	s_ashr_i32 s45, s44, 31
	s_lshl_b64 s[44:45], s[44:45], 12
	s_add_u32 s44, s64, s44
	s_addc_u32 s45, s65, s45
	v_lshlrev_b32_e32 v96, 2, v218
	v_or_b32_e32 v232, s42, v218
	v_ashrrev_i32_e32 v233, 31, v232
	v_lshlrev_b64 v[96:97], 2, v[232:233]
	v_lshl_add_u64 v[120:121], s[18:19], 0, v[96:97]
	v_add_co_u32_e32 v100, vcc, 0x5000, v120
	s_waitcnt lgkmcnt(0)
	s_barrier
	s_nop 0
	v_addc_co_u32_e32 v101, vcc, 0, v121, vcc
	v_add_co_u32_e32 v104, vcc, 0xb000, v120
	s_barrier
	s_nop 0
	v_addc_co_u32_e32 v105, vcc, 0, v121, vcc
	v_add_co_u32_e32 v112, vcc, s70, v120
	v_lshl_add_u64 v[124:125], s[22:23], 0, v[96:97]
	s_nop 0
	v_addc_co_u32_e32 v113, vcc, 0, v121, vcc
	v_add_co_u32_e32 v116, vcc, 0x8000, v120
	s_nop 0
	s_nop 0
	v_addc_co_u32_e32 v117, vcc, 0, v121, vcc
	v_add_co_u32_e32 v120, vcc, 0xd000, v120
	s_nop 0
	s_nop 0
	v_addc_co_u32_e32 v121, vcc, 0, v121, vcc
	v_add_co_u32_e32 v124, vcc, 0x2000, v124
	s_nop 0
	s_nop 0
	v_addc_co_u32_e32 v125, vcc, 0, v125, vcc
	v_mov_b32_e32 v192, 0
	v_mov_b32_e32 v198, 0
	v_mov_b32_e32 v199, 0
	v_mov_b32_e32 v200, 0
	v_mov_b32_e32 v201, 0
	v_mov_b32_e32 v206, 0
	v_mov_b32_e32 v207, 0
	v_mov_b32_e32 v208, 0
	v_mov_b32_e32 v209, 0
	v_mov_b32_e32 v194, 0
	v_mov_b32_e32 v195, 0
	v_mov_b32_e32 v196, 0
	v_mov_b32_e32 v197, 0
	v_mov_b32_e32 v202, 0
	v_mov_b32_e32 v203, 0
	v_mov_b32_e32 v204, 0
	v_mov_b32_e32 v205, 0
	s_and_saveexec_b64 s[42:43], s[26:27]
	s_cbranch_execz .LBB0_767
	ds_read_b128 v[202:205], v238
	ds_read_b128 v[206:209], v238 offset:512
	ds_read_b128 v[194:197], v238 offset:1024
	ds_read_b128 v[198:201], v238 offset:1536
.LBB0_767:
	s_or_b64 exec, exec, s[42:43]
	s_waitcnt lgkmcnt(0)
	v_mov_b32_dpp v198, v140 row_shr:1 row_mask:0xf bank_mask:0xf
	v_mov_b32_dpp v199, v141 row_shr:1 row_mask:0xf bank_mask:0xf
	s_waitcnt vmcnt(0)
	s_bitcmp1_b32 s99, 8
	s_cbranch_scc1 .Lcw758_nostage
	v_and_b32_e32 v107, 0xff, v219
	v_lshlrev_b32_e32 v107, 4, v107
	v_add_u32_e32 v107, 0x22000, v107
	ds_write_b128 v107, v[108:111]
.Lcw758_nostage:
	s_waitcnt lgkmcnt(0)
	s_barrier
	v_and_b32_e32 v253, 0xf0, v219
	v_lshlrev_b32_e32 v253, 4, v253
	v_add_u32_e32 v253, 0x22000, v253
	ds_read_b128 v[160:163], v253
	ds_read_b128 v[164:167], v253 offset:16
	ds_read_b128 v[168:171], v253 offset:32
	ds_read_b128 v[172:175], v253 offset:48
	ds_read_b128 v[176:179], v253 offset:64
	ds_read_b128 v[180:183], v253 offset:80
	ds_read_b128 v[184:187], v253 offset:96
	ds_read_b128 v[188:191], v253 offset:112
	ds_read_b128 v[96:99], v253 offset:128
	ds_read_b128 v[100:103], v253 offset:144
	ds_read_b128 v[104:107], v253 offset:160
	ds_read_b128 v[108:111], v253 offset:176
	ds_read_b128 v[112:115], v253 offset:192
	ds_read_b128 v[116:119], v253 offset:208
	ds_read_b128 v[120:123], v253 offset:224
	ds_read_b128 v[124:127], v253 offset:240
	s_waitcnt lgkmcnt(0)
	v_lshlrev_b32_e32 v253, 2, v218
	s_and_saveexec_b64 s[46:47], s[12:13]
	s_cbranch_execz .LBB0_763
	global_store_dwordx4 v253, v[156:159], s[44:45]
	global_store_dwordx4 v253, v[144:147], s[44:45] offset:1024
	global_store_dwordx4 v253, v[60:63], s[44:45] offset:16
	global_store_dwordx4 v253, v[48:51], s[44:45] offset:1040
	global_store_dwordx4 v253, v[152:155], s[44:45] offset:512
	global_store_dwordx4 v253, v[132:135], s[44:45] offset:1536
	global_store_dwordx4 v253, v[56:59], s[44:45] offset:528
	global_store_dwordx4 v253, v[36:39], s[44:45] offset:1552

;     __device__ __forceinline__ void operator()(AccRef acc, const Unit& u, int wr, int wc, int fr, int fq) const {
;     ...
;         float* rawu = raw + (size_t)(u.pm * 22 + u.pn) * 1024;
;         if (wr == 0 && fr == 0) {
; #pragma unroll
;             for (int bj = 0; bj < 2; ++bj)
; #pragma unroll
;                 for (int n = 0; n < 2; ++n) { *(f32x4*)(rawu + 0 * 256 + bj * 128 + clb + 4 * n) = acc[0][bj][0][n]; *(f32x4*)(rawu + 1 * 256 + bj * 128 + clb + 4 * n) = acc[0][bj][1][n]; }
;         }
;         if (wr == 1 && fr == 15) {
; #pragma unroll
;             for (int bj = 0; bj < 2; ++bj)
; #pragma unroll
;                 for (int n = 0; n < 2; ++n) { *(f32x4*)(rawu + 2 * 256 + bj * 128 + clb + 4 * n) = acc[1][bj][2][n]; *(f32x4*)(rawu + 3 * 256 + bj * 128 + clb + 4 * n) = acc[1][bj][3][n]; }
;         }
;         asm volatile("s_waitcnt lgkmcnt(0)" ::: "memory"); __builtin_amdgcn_s_barrier(); __builtin_amdgcn_s_barrier(); asm volatile("" ::: "memory");
;         const int hc0 = 128 * u.pn + clb, row0 = u.pm * 256 + wr * 64 + 4 * fr;
; #pragma unroll
;         for (int n = 0; n < 2; ++n) {
;             const f32x4 w0v = cwv[n][0], w1v = cwv[n][1], w2v = cwv[n][2], bvv = cwv[n][3], w0g = cwv[n][4], w1g = cwv[n][5], w2g = cwv[n][6], bvg = cwv[n][7];
; #pragma unroll
;             for (int ai = 0; ai < 2; ++ai) {
;                 if (n == 0 && ai == 0) {
;                     asm volatile("" ::: "memory");
;                     const float* cv = cw + hc0 + 4; const float* cg = cv + FH; const float* bp = cb + hc0 + 4;
;                     cwv[1][0] = *(const f32x4*)(cv); cwv[1][1] = *(const f32x4*)(cv + F2); cwv[1][2] = *(const f32x4*)(cv + 2 * F2); cwv[1][3] = *(const f32x4*)(bp);
;                     cwv[1][4] = *(const f32x4*)(cg); cwv[1][5] = *(const f32x4*)(cg + F2); cwv[1][6] = *(const f32x4*)(cg + 2 * F2); cwv[1][7] = *(const f32x4*)(bp + FH);
;                     asm volatile("" ::: "memory"); }
;                 f32x4 h2v = (f32x4){0.f, 0.f, 0.f, 0.f}, h3v = h2v, h2g = h2v, h3g = h2v;
;                 const int pb = ai * 2 + wr - 1;
;                 if (pb >= 0 && fr == 0) { const LAS float* xp = xch + (pb * 2) * 256 + clb + 4 * n;
;                     h2v = *(const LAS f32x4*)(xp); h3v = *(const LAS f32x4*)(xp + 256); h2g = *(const LAS f32x4*)(xp + 128); h3g = *(const LAS f32x4*)(xp + 256 + 128); }
.LBB0_1362:
	s_or_b64 exec, exec, s[46:47]
	s_mul_i32 s35, s42, 22
	s_add_i32 s46, s35, s43
	s_ashr_i32 s47, s46, 31
	s_lshl_b64 s[46:47], s[46:47], 12
	s_add_u32 s46, s64, s46
	s_addc_u32 s47, s65, s47
	v_lshlrev_b32_e32 v96, 2, v218
	v_or_b32_e32 v232, s44, v218
	v_ashrrev_i32_e32 v233, 31, v232
	v_lshlrev_b64 v[96:97], 2, v[232:233]
	v_lshl_add_u64 v[120:121], s[16:17], 0, v[96:97]
	v_add_co_u32_e32 v100, vcc, 0x5000, v120
	s_waitcnt lgkmcnt(0)
	s_barrier
	s_nop 0
	v_addc_co_u32_e32 v101, vcc, 0, v121, vcc
	v_add_co_u32_e32 v104, vcc, 0xb000, v120
	s_barrier
	s_nop 0
	v_addc_co_u32_e32 v105, vcc, 0, v121, vcc
	v_add_co_u32_e32 v112, vcc, s76, v120
	v_lshl_add_u64 v[124:125], s[22:23], 0, v[96:97]
	s_nop 0
	v_addc_co_u32_e32 v113, vcc, 0, v121, vcc
	v_add_co_u32_e32 v116, vcc, 0x8000, v120
	s_nop 0
	s_nop 0
	v_addc_co_u32_e32 v117, vcc, 0, v121, vcc
	v_add_co_u32_e32 v120, vcc, 0xd000, v120
	s_nop 0
	s_nop 0
	v_addc_co_u32_e32 v121, vcc, 0, v121, vcc
	v_add_co_u32_e32 v124, vcc, 0x2000, v124
	s_nop 0
	s_nop 0
	v_addc_co_u32_e32 v125, vcc, 0, v125, vcc
	v_mov_b32_e32 v192, 0
	v_mov_b32_e32 v198, 0
	v_mov_b32_e32 v199, 0
	v_mov_b32_e32 v200, 0
	v_mov_b32_e32 v201, 0
	v_mov_b32_e32 v206, 0
	v_mov_b32_e32 v207, 0
	v_mov_b32_e32 v208, 0
	v_mov_b32_e32 v209, 0
	v_mov_b32_e32 v194, 0
	v_mov_b32_e32 v195, 0
	v_mov_b32_e32 v196, 0
	v_mov_b32_e32 v197, 0
	v_mov_b32_e32 v202, 0
	v_mov_b32_e32 v203, 0
	v_mov_b32_e32 v204, 0
	v_mov_b32_e32 v205, 0
	s_and_saveexec_b64 s[44:45], s[28:29]
	s_cbranch_execz .LBB0_1368
	ds_read_b128 v[202:205], v238
	ds_read_b128 v[206:209], v238 offset:512
	ds_read_b128 v[194:197], v238 offset:1024
	ds_read_b128 v[198:201], v238 offset:1536
.LBB0_1368:
	s_or_b64 exec, exec, s[44:45]
	s_waitcnt lgkmcnt(0)
	v_mov_b32_dpp v198, v140 row_shr:1 row_mask:0xf bank_mask:0xf
	v_mov_b32_dpp v199, v141 row_shr:1 row_mask:0xf bank_mask:0xf
	s_waitcnt vmcnt(0)
	s_bitcmp1_b32 s99, 8
	s_cbranch_scc1 .Lcw1359_nostage
	v_and_b32_e32 v107, 0xff, v219
	v_lshlrev_b32_e32 v107, 4, v107
	v_add_u32_e32 v107, 0x22000, v107
	ds_write_b128 v107, v[108:111]
.Lcw1359_nostage:
	s_waitcnt lgkmcnt(0)
	s_barrier
	v_and_b32_e32 v253, 0xf0, v219
	v_lshlrev_b32_e32 v253, 4, v253
	v_add_u32_e32 v253, 0x22000, v253
	ds_read_b128 v[160:163], v253
	ds_read_b128 v[164:167], v253 offset:16
	ds_read_b128 v[168:171], v253 offset:32
	ds_read_b128 v[172:175], v253 offset:48
	ds_read_b128 v[176:179], v253 offset:64
	ds_read_b128 v[180:183], v253 offset:80
	ds_read_b128 v[184:187], v253 offset:96
	ds_read_b128 v[188:191], v253 offset:112
	ds_read_b128 v[96:99], v253 offset:128
	ds_read_b128 v[100:103], v253 offset:144
	ds_read_b128 v[104:107], v253 offset:160
	ds_read_b128 v[108:111], v253 offset:176
	ds_read_b128 v[112:115], v253 offset:192
	ds_read_b128 v[116:119], v253 offset:208
	ds_read_b128 v[120:123], v253 offset:224
	ds_read_b128 v[124:127], v253 offset:240
	s_waitcnt lgkmcnt(0)
	v_lshlrev_b32_e32 v253, 2, v218
	s_and_saveexec_b64 s[48:49], s[12:13]
	s_cbranch_execz .LBB0_1364
	global_store_dwordx4 v253, v[156:159], s[46:47]
	global_store_dwordx4 v253, v[144:147], s[46:47] offset:1024
	global_store_dwordx4 v253, v[60:63], s[46:47] offset:16
	global_store_dwordx4 v253, v[48:51], s[46:47] offset:1040
	global_store_dwordx4 v253, v[152:155], s[46:47] offset:512
	global_store_dwordx4 v253, v[132:135], s[46:47] offset:1536
	global_store_dwordx4 v253, v[56:59], s[46:47] offset:528
	global_store_dwordx4 v253, v[36:39], s[46:47] offset:1552

;     __device__ __forceinline__ void operator()(AccRef acc, const Unit& u, int wr, int wc, int fr, int fq) const {
;     ...
;         float* rawu = raw + (size_t)(u.pm * 22 + u.pn) * 1024;
;         if (wr == 0 && fr == 0) {
; #pragma unroll
;             for (int bj = 0; bj < 2; ++bj)
; #pragma unroll
;                 for (int n = 0; n < 2; ++n) { *(f32x4*)(rawu + 0 * 256 + bj * 128 + clb + 4 * n) = acc[0][bj][0][n]; *(f32x4*)(rawu + 1 * 256 + bj * 128 + clb + 4 * n) = acc[0][bj][1][n]; }
;         }
;         if (wr == 1 && fr == 15) {
; #pragma unroll
;             for (int bj = 0; bj < 2; ++bj)
; #pragma unroll
;                 for (int n = 0; n < 2; ++n) { *(f32x4*)(rawu + 2 * 256 + bj * 128 + clb + 4 * n) = acc[1][bj][2][n]; *(f32x4*)(rawu + 3 * 256 + bj * 128 + clb + 4 * n) = acc[1][bj][3][n]; }
;         }
;         asm volatile("s_waitcnt lgkmcnt(0)" ::: "memory"); __builtin_amdgcn_s_barrier(); __builtin_amdgcn_s_barrier(); asm volatile("" ::: "memory");
;         const int hc0 = 128 * u.pn + clb, row0 = u.pm * 256 + wr * 64 + 4 * fr;
; #pragma unroll
;         for (int n = 0; n < 2; ++n) {
;             const f32x4 w0v = cwv[n][0], w1v = cwv[n][1], w2v = cwv[n][2], bvv = cwv[n][3], w0g = cwv[n][4], w1g = cwv[n][5], w2g = cwv[n][6], bvg = cwv[n][7];
; #pragma unroll
;             for (int ai = 0; ai < 2; ++ai) {
;                 if (n == 0 && ai == 0) {
;                     asm volatile("" ::: "memory");
;                     const float* cv = cw + hc0 + 4; const float* cg = cv + FH; const float* bp = cb + hc0 + 4;
;                     cwv[1][0] = *(const f32x4*)(cv); cwv[1][1] = *(const f32x4*)(cv + F2); cwv[1][2] = *(const f32x4*)(cv + 2 * F2); cwv[1][3] = *(const f32x4*)(bp);
;                     cwv[1][4] = *(const f32x4*)(cg); cwv[1][5] = *(const f32x4*)(cg + F2); cwv[1][6] = *(const f32x4*)(cg + 2 * F2); cwv[1][7] = *(const f32x4*)(bp + FH);
;                     asm volatile("" ::: "memory"); }
;                 f32x4 h2v = (f32x4){0.f, 0.f, 0.f, 0.f}, h3v = h2v, h2g = h2v, h3g = h2v;
;                 const int pb = ai * 2 + wr - 1;
;                 if (pb >= 0 && fr == 0) { const LAS float* xp = xch + (pb * 2) * 256 + clb + 4 * n;
;                     h2v = *(const LAS f32x4*)(xp); h3v = *(const LAS f32x4*)(xp + 256); h2g = *(const LAS f32x4*)(xp + 128); h3g = *(const LAS f32x4*)(xp + 256 + 128); }
.LBB0_1943:
	s_or_b64 exec, exec, s[38:39]
	s_mul_i32 s25, s34, 22
	s_add_i32 s38, s25, s35
	s_ashr_i32 s39, s38, 31
	s_lshl_b64 s[38:39], s[38:39], 12
	s_add_u32 s38, s64, s38
	s_addc_u32 s39, s65, s39
	v_lshlrev_b32_e32 v96, 2, v218
	v_or_b32_e32 v232, s36, v218
	v_ashrrev_i32_e32 v233, 31, v232
	v_lshlrev_b64 v[96:97], 2, v[232:233]
	v_lshl_add_u64 v[120:121], s[12:13], 0, v[96:97]
	v_add_co_u32_e32 v100, vcc, 0x5000, v120
	s_waitcnt lgkmcnt(0)
	s_barrier
	s_nop 0
	v_addc_co_u32_e32 v101, vcc, 0, v121, vcc
	v_add_co_u32_e32 v104, vcc, 0xb000, v120
	s_barrier
	s_nop 0
	v_addc_co_u32_e32 v105, vcc, 0, v121, vcc
	v_add_co_u32_e32 v112, vcc, s49, v120
	v_lshl_add_u64 v[124:125], s[14:15], 0, v[96:97]
	s_nop 0
	v_addc_co_u32_e32 v113, vcc, 0, v121, vcc
	v_add_co_u32_e32 v116, vcc, 0x8000, v120
	s_nop 0
	s_nop 0
	v_addc_co_u32_e32 v117, vcc, 0, v121, vcc
	v_add_co_u32_e32 v120, vcc, 0xd000, v120
	s_nop 0
	s_nop 0
	v_addc_co_u32_e32 v121, vcc, 0, v121, vcc
	v_add_co_u32_e32 v124, vcc, 0x2000, v124
	s_nop 0
	s_nop 0
	v_addc_co_u32_e32 v125, vcc, 0, v125, vcc
	v_mov_b32_e32 v192, 0
	v_mov_b32_e32 v198, 0
	v_mov_b32_e32 v199, 0
	v_mov_b32_e32 v200, 0
	v_mov_b32_e32 v201, 0
	v_mov_b32_e32 v206, 0
	v_mov_b32_e32 v207, 0
	v_mov_b32_e32 v208, 0
	v_mov_b32_e32 v209, 0
	v_mov_b32_e32 v194, 0
	v_mov_b32_e32 v195, 0
	v_mov_b32_e32 v196, 0
	v_mov_b32_e32 v197, 0
	v_mov_b32_e32 v202, 0
	v_mov_b32_e32 v203, 0
	v_mov_b32_e32 v204, 0
	v_mov_b32_e32 v205, 0
	s_and_saveexec_b64 s[36:37], s[20:21]
	s_cbranch_execz .LBB0_1949
	ds_read_b128 v[202:205], v237
	ds_read_b128 v[206:209], v237 offset:512
	ds_read_b128 v[194:197], v237 offset:1024
	ds_read_b128 v[198:201], v237 offset:1536

;     __device__ __forceinline__ void operator()(AccRef acc, const Unit& u, int wr, int wc, int fr, int fq) const {
;     ...
;         if (wr == 0 && fr == 0) {
; #pragma unroll
;             for (int bj = 0; bj < 2; ++bj)
; #pragma unroll
;                 for (int n = 0; n < 2; ++n) { *(f32x4*)(rawu + 0 * 256 + bj * 128 + clb + 4 * n) = acc[0][bj][0][n]; *(f32x4*)(rawu + 1 * 256 + bj * 128 + clb + 4 * n) = acc[0][bj][1][n]; }
;     ...
;             const f32x4 w0v = cwv[n][0], w1v = cwv[n][1], w2v = cwv[n][2], bvv = cwv[n][3], w0g = cwv[n][4], w1g = cwv[n][5], w2g = cwv[n][6], bvg = cwv[n][7];
; #pragma unroll
;             for (int ai = 0; ai < 2; ++ai) {
;                 if (n == 0 && ai == 0) {
;                     asm volatile("" ::: "memory");
;                     const float* cv = cw + hc0 + 4; const float* cg = cv + FH; const float* bp = cb + hc0 + 4;
;                     cwv[1][0] = *(const f32x4*)(cv); cwv[1][1] = *(const f32x4*)(cv + F2); cwv[1][2] = *(const f32x4*)(cv + 2 * F2); cwv[1][3] = *(const f32x4*)(bp);
;                     cwv[1][4] = *(const f32x4*)(cg); cwv[1][5] = *(const f32x4*)(cg + F2); cwv[1][6] = *(const f32x4*)(cg + 2 * F2); cwv[1][7] = *(const f32x4*)(bp + FH);
.Lcw1940_nostage:
	s_waitcnt lgkmcnt(0)
	s_barrier
	v_and_b32_e32 v253, 0xf0, v219
	v_lshlrev_b32_e32 v253, 4, v253
	v_add_u32_e32 v253, 0x22000, v253
	ds_read_b128 v[160:163], v253
	ds_read_b128 v[164:167], v253 offset:16
	ds_read_b128 v[168:171], v253 offset:32
	ds_read_b128 v[172:175], v253 offset:48
	ds_read_b128 v[176:179], v253 offset:64
	ds_read_b128 v[180:183], v253 offset:80
	ds_read_b128 v[184:187], v253 offset:96
	ds_read_b128 v[188:191], v253 offset:112
	ds_read_b128 v[96:99], v253 offset:128
	ds_read_b128 v[100:103], v253 offset:144
	ds_read_b128 v[104:107], v253 offset:160
	ds_read_b128 v[108:111], v253 offset:176
	ds_read_b128 v[112:115], v253 offset:192
	ds_read_b128 v[116:119], v253 offset:208
	ds_read_b128 v[120:123], v253 offset:224
	ds_read_b128 v[124:127], v253 offset:240
	s_waitcnt lgkmcnt(0)
	v_lshlrev_b32_e32 v253, 2, v218
	s_and_saveexec_b64 s[40:41], s[8:9]
	s_cbranch_execz .LBB0_1945
	global_store_dwordx4 v253, v[156:159], s[38:39]
	global_store_dwordx4 v253, v[144:147], s[38:39] offset:1024
	global_store_dwordx4 v253, v[60:63], s[38:39] offset:16
	global_store_dwordx4 v253, v[48:51], s[38:39] offset:1040
	global_store_dwordx4 v253, v[152:155], s[38:39] offset:512
	global_store_dwordx4 v253, v[132:135], s[38:39] offset:1536
	global_store_dwordx4 v253, v[56:59], s[38:39] offset:528
	global_store_dwordx4 v253, v[36:39], s[38:39] offset:1552
